# T21 on all four in-proj epilogue paths (u/v/q/k): bf16 stores as dwordx4 via v_permlane16_swap
# speedup vs baseline: 1.0148x; 1.0051x over previous
.LBB0_630:
	v_cvt_pk_bf16_f32 v228, v170, v171
	v_cvt_pk_bf16_f32 v229, v172, v173
	v_mbcnt_lo_u32_b32 v0, -1, 0
	v_mbcnt_hi_u32_b32 v0, -1, v0
	v_bfe_u32 v0, v0, 4, 1
	v_mul_u32_u24_e32 v0, 24, v0
	v_lshl_add_u64 v[236:237], v[210:211], 0, v[0:1]
	v_cvt_pk_bf16_f32 v230, v174, v175
	v_cvt_pk_bf16_f32 v231, v176, v177
	s_nop 1
	v_permlane16_swap_b32_e32 v228, v230
	v_permlane16_swap_b32_e32 v229, v231
	global_store_dwordx4 v[236:237], v[228:231], off
	v_cvt_pk_bf16_f32 v232, v162, v163
	v_cvt_pk_bf16_f32 v233, v164, v165
	v_cvt_pk_bf16_f32 v234, v166, v167
	v_cvt_pk_bf16_f32 v235, v168, v169
	s_nop 1
	v_permlane16_swap_b32_e32 v232, v234
	v_permlane16_swap_b32_e32 v233, v235
	global_store_dwordx4 v[236:237], v[232:235], off offset:64
	v_pk_fma_f32 v[162:163], v[112:113], v[208:209], v[160:161] op_sel_hi:[1,0,1]
	v_pk_fma_f32 v[164:165], v[110:111], v[208:209], v[158:159] op_sel_hi:[1,0,1]
	v_mul_f32_e32 v171, v163, v163
	v_mul_f32_e32 v170, v165, v165
	v_pk_fma_f32 v[166:167], v[108:109], v[208:209], v[156:157] op_sel_hi:[1,0,1]
	v_pk_fma_f32 v[168:169], v[106:107], v[208:209], v[154:155] op_sel_hi:[1,0,1]
	v_fmac_f32_e32 v170, v164, v164
	v_fmac_f32_e32 v171, v162, v162
	v_add_f32_e32 v170, v170, v171
	v_mul_f32_e32 v171, v169, v169
	v_mul_f32_e32 v172, v167, v167
	v_fmac_f32_e32 v171, v168, v168
	v_fmac_f32_e32 v172, v166, v166
	v_pk_fma_f32 v[174:175], v[104:105], v[208:209], v[152:153] op_sel_hi:[1,0,1]
	v_pk_fma_f32 v[176:177], v[102:103], v[208:209], v[150:151] op_sel_hi:[1,0,1]
	v_add_f32_e32 v171, v171, v172
	v_add_f32_e32 v170, v170, v171
	v_mul_f32_e32 v171, v177, v177
	v_mul_f32_e32 v172, v175, v175
	v_fmac_f32_e32 v171, v176, v176
	v_fmac_f32_e32 v172, v174, v174
	v_pk_fma_f32 v[212:213], v[100:101], v[208:209], v[148:149] op_sel_hi:[1,0,1]
	v_pk_fma_f32 v[228:229], v[98:99], v[208:209], v[146:147] op_sel_hi:[1,0,1]
	v_add_f32_e32 v171, v171, v172
	v_add_f32_e32 v170, v170, v171
	v_mul_f32_e32 v171, v229, v229
	v_mul_f32_e32 v172, v213, v213
	v_fmac_f32_e32 v171, v228, v228
	v_fmac_f32_e32 v172, v212, v212
	v_add_f32_e32 v171, v171, v172
	v_add_f32_e32 v170, v170, v171
	v_mov_b32_e32 v171, v170
	s_nop 1
	v_permlane16_swap_b32_e32 v170, v171
	v_add_f32_e32 v170, v170, v171
	v_mov_b32_e32 v171, v170
	s_nop 1
	v_permlane32_swap_b32_e32 v170, v171
	v_add_f32_e32 v170, v170, v171
	v_fmamk_f32 v170, v170, 0x3c800000, v223
	v_rsq_f32_e32 v222, v170
	v_add_u32_e32 v205, 16, v216
	v_and_b32_e32 v207, 63, v205
	v_mov_b64_e32 v[210:211], v[194:195]
	v_pk_mul_f32 v[164:165], v[164:165], v[222:223] op_sel_hi:[1,0]
	v_pk_mul_f32 v[162:163], v[162:163], v[222:223] op_sel_hi:[1,0]
	v_pk_mul_f32 v[170:171], v[130:131], v[164:165]
	v_pk_mul_f32 v[172:173], v[132:133], v[162:163]
	v_pk_mul_f32 v[162:163], v[168:169], v[222:223] op_sel_hi:[1,0]
	v_pk_mul_f32 v[164:165], v[166:167], v[222:223] op_sel_hi:[1,0]
	v_pk_mul_f32 v[166:167], v[134:135], v[162:163]
	v_pk_mul_f32 v[168:169], v[136:137], v[164:165]
	v_pk_mul_f32 v[162:163], v[176:177], v[222:223] op_sel_hi:[1,0]
	v_pk_mul_f32 v[164:165], v[174:175], v[222:223] op_sel_hi:[1,0]
	v_pk_mul_f32 v[174:175], v[228:229], v[222:223] op_sel_hi:[1,0]
	v_pk_mul_f32 v[176:177], v[212:213], v[222:223] op_sel_hi:[1,0]
	v_cvt_f32_ubyte0_e32 v212, v207
	v_mov_b64_e32 v[208:209], v[192:193]
	v_pk_mul_f32 v[164:165], v[140:141], v[164:165]
	v_pk_mul_f32 v[162:163], v[138:139], v[162:163]
	v_pk_mul_f32 v[176:177], v[144:145], v[176:177]
	v_pk_mul_f32 v[174:175], v[142:143], v[174:175]
	s_and_b64 vcc, exec, s[44:45]
	v_mul_f32_e32 v245, v220, v212
	v_mul_f32_e32 v243, v219, v212
	v_mul_f32_e32 v241, v218, v212
	v_mul_f32_e32 v213, v197, v212
	s_cbranch_vccnz .LBB0_632
	v_ashrrev_i32_e32 v205, 6, v205
	v_cvt_f32_i32_e32 v205, v205
	v_mul_f32_e32 v207, v220, v205
	v_mul_f32_e32 v222, v219, v205
	v_floor_f32_e32 v207, v207
	v_floor_f32_e32 v222, v222
	v_fma_f32 v207, v220, v205, -v207
	v_sin_f32_e32 v228, v207
	v_cos_f32_e32 v230, v207
	v_fma_f32 v207, v219, v205, -v222
	v_sin_f32_e32 v229, v207
	v_cos_f32_e32 v231, v207
	v_mul_f32_e32 v207, v218, v205
	v_floor_f32_e32 v207, v207
	v_pk_mul_f32 v[232:233], v[228:229], v[166:167]
	v_pk_mul_f32 v[166:167], v[230:231], v[166:167]
	v_mul_f32_e32 v224, v197, v205
	v_fma_f32 v207, v218, v205, -v207
	v_floor_f32_e32 v224, v224
	v_pk_fma_f32 v[230:231], v[230:231], v[170:171], v[232:233] neg_lo:[0,0,1] neg_hi:[0,0,1]
	v_pk_fma_f32 v[166:167], v[228:229], v[170:171], v[166:167]
	v_floor_f32_e32 v170, v245
	v_cos_f32_e32 v222, v207
	v_sin_f32_e32 v207, v207
	v_fma_f32 v205, v197, v205, -v224
	v_fma_f32 v171, v220, v212, -v170
	v_sin_f32_e32 v247, v205
	v_cos_f32_e32 v246, v205
	v_sin_f32_e32 v170, v171
	v_cos_f32_e32 v228, v171
	v_floor_f32_e32 v171, v243
	v_fma_f32 v205, v219, v212, -v171
	v_sin_f32_e32 v171, v205
	v_cos_f32_e32 v229, v205
	v_floor_f32_e32 v205, v241
	v_mul_f32_e32 v234, v222, v172
	v_mul_f32_e32 v236, v207, v168
	v_mul_f32_e32 v250, v222, v168
	v_mov_b32_e32 v168, v173
	v_fma_f32 v205, v218, v212, -v205
	v_floor_f32_e32 v222, v213
	v_mul_f32_e32 v248, v207, v172
	v_pk_mul_f32 v[172:173], v[246:247], v[168:169]
	v_cos_f32_e32 v207, v205
	v_sin_f32_e32 v205, v205
	v_fma_f32 v222, v197, v212, -v222
	v_mov_b32_e32 v235, v172
	v_mov_b32_e32 v237, v173
	v_mov_b32_e32 v172, v247
	v_mov_b32_e32 v173, v246
	v_sin_f32_e32 v247, v222
	v_cos_f32_e32 v246, v222
	v_pk_mul_f32 v[168:169], v[172:173], v[168:169]
	v_pk_add_f32 v[172:173], v[234:235], v[236:237] neg_lo:[0,1] neg_hi:[0,1]
	v_mov_b32_e32 v249, v168
	v_mov_b32_e32 v251, v169
	v_pk_add_f32 v[168:169], v[248:249], v[250:251]
	v_mul_f32_e32 v236, v205, v176
	v_mul_f32_e32 v250, v207, v176
	v_mov_b32_e32 v176, v165
	v_mul_f32_e32 v234, v207, v164
	v_mul_f32_e32 v248, v205, v164
	v_pk_mul_f32 v[164:165], v[246:247], v[176:177]
	v_pk_mul_f32 v[232:233], v[170:171], v[174:175]
	v_mov_b32_e32 v235, v164
	v_mov_b32_e32 v237, v165
	v_mov_b32_e32 v164, v247
	v_mov_b32_e32 v165, v246
	v_pk_mul_f32 v[164:165], v[164:165], v[176:177]
	v_pk_mul_f32 v[174:175], v[228:229], v[174:175]
	v_mov_b32_e32 v249, v164
	v_mov_b32_e32 v251, v165
	v_pk_fma_f32 v[228:229], v[228:229], v[162:163], v[232:233] neg_lo:[0,0,1] neg_hi:[0,0,1]
	v_pk_add_f32 v[164:165], v[234:235], v[236:237] neg_lo:[0,1] neg_hi:[0,1]
	v_pk_fma_f32 v[174:175], v[170:171], v[162:163], v[174:175]
	v_pk_add_f32 v[176:177], v[248:249], v[250:251]
	v_mov_b32_e32 v170, v230
	v_mov_b32_e32 v171, v231
	v_mov_b32_e32 v162, v228
	v_mov_b32_e32 v163, v229

.LBB0_634:
	v_cvt_pk_bf16_f32 v228, v170, v171
	v_cvt_pk_bf16_f32 v229, v172, v173
	v_add_co_u32_e32 v172, vcc, 0x1000, v208
	v_xor_b32_e32 v203, 32, v203
	s_nop 0
	v_addc_co_u32_e32 v173, vcc, 0, v209, vcc
	v_mbcnt_lo_u32_b32 v0, -1, 0
	v_mbcnt_hi_u32_b32 v0, -1, v0
	v_bfe_u32 v0, v0, 4, 1
	v_mul_u32_u24_e32 v0, 24, v0
	v_lshl_add_u64 v[236:237], v[172:173], 0, v[0:1]
	v_cvt_pk_bf16_f32 v230, v166, v167
	v_cvt_pk_bf16_f32 v231, v168, v169
	s_nop 1
	v_permlane16_swap_b32_e32 v228, v230
	v_permlane16_swap_b32_e32 v229, v231
	global_store_dwordx4 v[236:237], v[228:231], off
	v_cvt_pk_bf16_f32 v232, v162, v163
	v_cvt_pk_bf16_f32 v233, v164, v165
	v_cvt_pk_bf16_f32 v234, v174, v175
	v_cvt_pk_bf16_f32 v235, v176, v177
	s_nop 1
	v_permlane16_swap_b32_e32 v232, v234
	v_permlane16_swap_b32_e32 v233, v235
	global_store_dwordx4 v[236:237], v[232:235], off offset:64
	v_pk_fma_f32 v[162:163], v[96:97], v[206:207], v[160:161] op_sel_hi:[1,0,1]
	v_pk_fma_f32 v[164:165], v[94:95], v[206:207], v[158:159] op_sel_hi:[1,0,1]
	v_mul_f32_e32 v171, v163, v163
	v_mul_f32_e32 v170, v165, v165
	v_pk_fma_f32 v[166:167], v[92:93], v[206:207], v[156:157] op_sel_hi:[1,0,1]
	v_pk_fma_f32 v[168:169], v[90:91], v[206:207], v[154:155] op_sel_hi:[1,0,1]
	v_fmac_f32_e32 v170, v164, v164
	v_fmac_f32_e32 v171, v162, v162
	v_add_f32_e32 v170, v170, v171
	v_mul_f32_e32 v171, v169, v169
	v_mul_f32_e32 v172, v167, v167
	v_fmac_f32_e32 v171, v168, v168
	v_fmac_f32_e32 v172, v166, v166
	v_pk_fma_f32 v[174:175], v[88:89], v[206:207], v[152:153] op_sel_hi:[1,0,1]
	v_pk_fma_f32 v[176:177], v[86:87], v[206:207], v[150:151] op_sel_hi:[1,0,1]
	v_add_f32_e32 v171, v171, v172
	v_add_f32_e32 v170, v170, v171
	v_mul_f32_e32 v171, v177, v177
	v_mul_f32_e32 v172, v175, v175
	v_fmac_f32_e32 v171, v176, v176
	v_fmac_f32_e32 v172, v174, v174
	v_pk_fma_f32 v[210:211], v[84:85], v[206:207], v[148:149] op_sel_hi:[1,0,1]
	v_pk_fma_f32 v[228:229], v[82:83], v[206:207], v[146:147] op_sel_hi:[1,0,1]
	v_add_f32_e32 v171, v171, v172
	v_add_f32_e32 v170, v170, v171
	v_mul_f32_e32 v171, v229, v229
	v_mul_f32_e32 v172, v211, v211
	v_fmac_f32_e32 v171, v228, v228
	v_fmac_f32_e32 v172, v210, v210
	v_add_f32_e32 v171, v171, v172
	v_add_f32_e32 v170, v170, v171
	v_mov_b32_e32 v171, v170
	s_nop 1
	v_permlane16_swap_b32_e32 v170, v171
	v_add_f32_e32 v170, v170, v171
	v_mov_b32_e32 v171, v170
	s_nop 1
	v_permlane32_swap_b32_e32 v170, v171
	v_add_f32_e32 v170, v170, v171
	v_fmamk_f32 v170, v170, 0x3c800000, v223
	v_rsq_f32_e32 v222, v170
	v_mov_b64_e32 v[208:209], v[194:195]
	v_mov_b64_e32 v[206:207], v[192:193]
	s_and_b64 vcc, exec, s[44:45]
	v_pk_mul_f32 v[164:165], v[164:165], v[222:223] op_sel_hi:[1,0]
	v_pk_mul_f32 v[162:163], v[162:163], v[222:223] op_sel_hi:[1,0]
	v_pk_mul_f32 v[170:171], v[130:131], v[164:165]
	v_pk_mul_f32 v[172:173], v[132:133], v[162:163]
	v_pk_mul_f32 v[162:163], v[168:169], v[222:223] op_sel_hi:[1,0]
	v_pk_mul_f32 v[164:165], v[166:167], v[222:223] op_sel_hi:[1,0]
	v_pk_mul_f32 v[166:167], v[134:135], v[162:163]
	v_pk_mul_f32 v[168:169], v[136:137], v[164:165]
	v_pk_mul_f32 v[162:163], v[176:177], v[222:223] op_sel_hi:[1,0]
	v_pk_mul_f32 v[164:165], v[174:175], v[222:223] op_sel_hi:[1,0]
	v_pk_mul_f32 v[174:175], v[228:229], v[222:223] op_sel_hi:[1,0]
	v_pk_mul_f32 v[176:177], v[210:211], v[222:223] op_sel_hi:[1,0]
	v_cvt_f32_ubyte0_e32 v210, v203
	v_pk_mul_f32 v[164:165], v[140:141], v[164:165]
	v_pk_mul_f32 v[162:163], v[138:139], v[162:163]
	v_pk_mul_f32 v[176:177], v[144:145], v[176:177]
	v_pk_mul_f32 v[174:175], v[142:143], v[174:175]
	v_mul_f32_e32 v247, v220, v210
	v_mul_f32_e32 v246, v219, v210
	v_mul_f32_e32 v242, v218, v210
	v_mul_f32_e32 v211, v197, v210
	s_cbranch_vccnz .LBB0_636
	v_add_u32_e32 v203, 32, v216
	v_ashrrev_i32_e32 v203, 6, v203
	v_cvt_f32_i32_e32 v203, v203
	v_mul_f32_e32 v205, v220, v203
	v_mul_f32_e32 v222, v219, v203
	v_floor_f32_e32 v205, v205
	v_floor_f32_e32 v222, v222
	v_fma_f32 v205, v220, v203, -v205
	v_sin_f32_e32 v228, v205
	v_cos_f32_e32 v230, v205
	v_fma_f32 v205, v219, v203, -v222
	v_sin_f32_e32 v229, v205
	v_cos_f32_e32 v231, v205
	v_mul_f32_e32 v205, v218, v203
	v_floor_f32_e32 v205, v205
	v_pk_mul_f32 v[232:233], v[228:229], v[166:167]
	v_pk_mul_f32 v[166:167], v[230:231], v[166:167]
	v_mul_f32_e32 v224, v197, v203
	v_fma_f32 v205, v218, v203, -v205
	v_floor_f32_e32 v224, v224
	v_pk_fma_f32 v[230:231], v[230:231], v[170:171], v[232:233] neg_lo:[0,0,1] neg_hi:[0,0,1]
	v_pk_fma_f32 v[166:167], v[228:229], v[170:171], v[166:167]
	v_floor_f32_e32 v170, v247
	v_cos_f32_e32 v222, v205
	v_sin_f32_e32 v205, v205
	v_fma_f32 v203, v197, v203, -v224
	v_fma_f32 v171, v220, v210, -v170
	v_sin_f32_e32 v249, v203
	v_cos_f32_e32 v248, v203
	v_sin_f32_e32 v170, v171
	v_cos_f32_e32 v228, v171
	v_floor_f32_e32 v171, v246
	v_fma_f32 v203, v219, v210, -v171
	v_sin_f32_e32 v171, v203
	v_cos_f32_e32 v229, v203
	v_floor_f32_e32 v203, v242
	v_mul_f32_e32 v234, v222, v172
	v_mul_f32_e32 v236, v205, v168
	v_mul_f32_e32 v252, v222, v168
	v_mov_b32_e32 v168, v173
	v_fma_f32 v203, v218, v210, -v203
	v_floor_f32_e32 v222, v211
	v_mul_f32_e32 v250, v205, v172
	v_pk_mul_f32 v[172:173], v[248:249], v[168:169]
	v_cos_f32_e32 v205, v203
	v_sin_f32_e32 v203, v203
	v_fma_f32 v222, v197, v210, -v222
	v_mov_b32_e32 v235, v172
	v_mov_b32_e32 v237, v173
	v_mov_b32_e32 v172, v249
	v_mov_b32_e32 v173, v248
	v_sin_f32_e32 v249, v222
	v_cos_f32_e32 v248, v222
	v_pk_mul_f32 v[168:169], v[172:173], v[168:169]
	v_pk_add_f32 v[172:173], v[234:235], v[236:237] neg_lo:[0,1] neg_hi:[0,1]
	v_mov_b32_e32 v251, v168
	v_mov_b32_e32 v253, v169
	v_pk_add_f32 v[168:169], v[250:251], v[252:253]
	v_mul_f32_e32 v236, v203, v176
	v_mul_f32_e32 v252, v205, v176
	v_mov_b32_e32 v176, v165
	v_mul_f32_e32 v234, v205, v164
	v_mul_f32_e32 v250, v203, v164
	v_pk_mul_f32 v[164:165], v[248:249], v[176:177]
	v_pk_mul_f32 v[232:233], v[170:171], v[174:175]
	v_mov_b32_e32 v235, v164
	v_mov_b32_e32 v237, v165
	v_mov_b32_e32 v164, v249
	v_mov_b32_e32 v165, v248
	v_pk_mul_f32 v[164:165], v[164:165], v[176:177]
	v_pk_mul_f32 v[174:175], v[228:229], v[174:175]
	v_mov_b32_e32 v251, v164
	v_mov_b32_e32 v253, v165
	v_pk_fma_f32 v[228:229], v[228:229], v[162:163], v[232:233] neg_lo:[0,0,1] neg_hi:[0,0,1]
	v_pk_add_f32 v[164:165], v[234:235], v[236:237] neg_lo:[0,1] neg_hi:[0,1]
	v_pk_fma_f32 v[174:175], v[170:171], v[162:163], v[174:175]
	v_pk_add_f32 v[176:177], v[250:251], v[252:253]
	v_mov_b32_e32 v170, v230
	v_mov_b32_e32 v171, v231
	v_mov_b32_e32 v162, v228
	v_mov_b32_e32 v163, v229

.LBB0_638:
	v_cvt_pk_bf16_f32 v228, v170, v171
	v_cvt_pk_bf16_f32 v229, v172, v173
	v_add_co_u32_e32 v172, vcc, 0x2000, v206
	v_pk_fma_f32 v[208:209], v[68:69], v[204:205], v[148:149] op_sel_hi:[1,0,1]
	s_nop 0
	v_addc_co_u32_e32 v173, vcc, 0, v207, vcc
	v_mbcnt_lo_u32_b32 v0, -1, 0
	v_mbcnt_hi_u32_b32 v0, -1, v0
	v_bfe_u32 v0, v0, 4, 1
	v_mul_u32_u24_e32 v0, 24, v0
	v_lshl_add_u64 v[236:237], v[172:173], 0, v[0:1]
	v_cvt_pk_bf16_f32 v230, v166, v167
	v_cvt_pk_bf16_f32 v231, v168, v169
	s_nop 1
	v_permlane16_swap_b32_e32 v228, v230
	v_permlane16_swap_b32_e32 v229, v231
	global_store_dwordx4 v[236:237], v[228:231], off
	v_cvt_pk_bf16_f32 v232, v162, v163
	v_cvt_pk_bf16_f32 v233, v164, v165
	v_cvt_pk_bf16_f32 v234, v174, v175
	v_cvt_pk_bf16_f32 v235, v176, v177
	s_nop 1
	v_permlane16_swap_b32_e32 v232, v234
	v_permlane16_swap_b32_e32 v233, v235
	global_store_dwordx4 v[236:237], v[232:235], off offset:64
	v_pk_fma_f32 v[162:163], v[80:81], v[204:205], v[160:161] op_sel_hi:[1,0,1]
	v_pk_fma_f32 v[164:165], v[78:79], v[204:205], v[158:159] op_sel_hi:[1,0,1]
	v_mul_f32_e32 v171, v163, v163
	v_mul_f32_e32 v170, v165, v165
	v_pk_fma_f32 v[166:167], v[76:77], v[204:205], v[156:157] op_sel_hi:[1,0,1]
	v_pk_fma_f32 v[168:169], v[74:75], v[204:205], v[154:155] op_sel_hi:[1,0,1]
	v_fmac_f32_e32 v170, v164, v164
	v_fmac_f32_e32 v171, v162, v162
	v_add_f32_e32 v170, v170, v171
	v_mul_f32_e32 v171, v169, v169
	v_mul_f32_e32 v172, v167, v167
	v_fmac_f32_e32 v171, v168, v168
	v_fmac_f32_e32 v172, v166, v166
	v_pk_fma_f32 v[174:175], v[72:73], v[204:205], v[152:153] op_sel_hi:[1,0,1]
	v_pk_fma_f32 v[176:177], v[70:71], v[204:205], v[150:151] op_sel_hi:[1,0,1]
	v_add_f32_e32 v171, v171, v172
	v_add_f32_e32 v170, v170, v171
	v_mul_f32_e32 v171, v177, v177
	v_mul_f32_e32 v172, v175, v175
	v_fmac_f32_e32 v171, v176, v176
	v_fmac_f32_e32 v172, v174, v174
	v_pk_fma_f32 v[228:229], v[66:67], v[204:205], v[146:147] op_sel_hi:[1,0,1]
	v_add_f32_e32 v171, v171, v172
	v_add_f32_e32 v170, v170, v171
	v_mul_f32_e32 v171, v229, v229
	v_mul_f32_e32 v172, v209, v209
	v_fmac_f32_e32 v171, v228, v228
	v_fmac_f32_e32 v172, v208, v208
	v_add_f32_e32 v171, v171, v172
	v_add_f32_e32 v170, v170, v171
	v_mov_b32_e32 v171, v170
	s_nop 1
	v_permlane16_swap_b32_e32 v170, v171
	v_add_f32_e32 v170, v170, v171
	v_mov_b32_e32 v171, v170
	s_nop 1
	v_permlane32_swap_b32_e32 v170, v171
	v_add_f32_e32 v170, v170, v171
	v_fmamk_f32 v170, v170, 0x3c800000, v223
	v_rsq_f32_e32 v222, v170
	v_add_u32_e32 v203, 48, v216
	v_and_b32_e32 v224, 63, v203
	v_mov_b64_e32 v[206:207], v[194:195]
	v_pk_mul_f32 v[164:165], v[164:165], v[222:223] op_sel_hi:[1,0]
	v_pk_mul_f32 v[162:163], v[162:163], v[222:223] op_sel_hi:[1,0]
	v_pk_mul_f32 v[170:171], v[130:131], v[164:165]
	v_pk_mul_f32 v[172:173], v[132:133], v[162:163]
	v_pk_mul_f32 v[162:163], v[168:169], v[222:223] op_sel_hi:[1,0]
	v_pk_mul_f32 v[164:165], v[166:167], v[222:223] op_sel_hi:[1,0]
	v_pk_mul_f32 v[166:167], v[134:135], v[162:163]
	v_pk_mul_f32 v[168:169], v[136:137], v[164:165]
	v_pk_mul_f32 v[162:163], v[176:177], v[222:223] op_sel_hi:[1,0]
	v_pk_mul_f32 v[164:165], v[174:175], v[222:223] op_sel_hi:[1,0]
	v_pk_mul_f32 v[174:175], v[228:229], v[222:223] op_sel_hi:[1,0]
	v_pk_mul_f32 v[176:177], v[208:209], v[222:223] op_sel_hi:[1,0]
	v_cvt_f32_ubyte0_e32 v208, v224
	v_mov_b64_e32 v[204:205], v[192:193]
	v_pk_mul_f32 v[164:165], v[140:141], v[164:165]
	v_pk_mul_f32 v[162:163], v[138:139], v[162:163]
	v_pk_mul_f32 v[176:177], v[144:145], v[176:177]
	v_pk_mul_f32 v[174:175], v[142:143], v[174:175]
	s_and_b64 vcc, exec, s[44:45]
	v_mul_f32_e32 v249, v220, v208
	v_mul_f32_e32 v248, v219, v208
	v_mul_f32_e32 v244, v218, v208
	v_mul_f32_e32 v209, v197, v208
	s_cbranch_vccnz .LBB0_640
	v_ashrrev_i32_e32 v203, 6, v203
	v_cvt_f32_i32_e32 v203, v203
	v_mul_f32_e32 v222, v220, v203
	v_mul_f32_e32 v224, v219, v203
	v_floor_f32_e32 v222, v222
	v_floor_f32_e32 v224, v224
	v_fma_f32 v222, v220, v203, -v222
	v_sin_f32_e32 v228, v222
	v_cos_f32_e32 v230, v222
	v_fma_f32 v222, v219, v203, -v224
	v_sin_f32_e32 v229, v222
	v_cos_f32_e32 v231, v222
	v_mul_f32_e32 v222, v218, v203
	v_floor_f32_e32 v222, v222
	v_mul_f32_e32 v225, v197, v203
	v_fma_f32 v222, v218, v203, -v222
	v_floor_f32_e32 v225, v225
	v_cos_f32_e32 v224, v222
	v_sin_f32_e32 v222, v222
	v_fma_f32 v203, v197, v203, -v225
	v_sin_f32_e32 v251, v203
	v_cos_f32_e32 v250, v203
	v_mul_f32_e32 v234, v224, v172
	v_mul_f32_e32 v236, v222, v168
	v_mul_f32_e32 v224, v224, v168
	v_mov_b32_e32 v168, v173
	v_mul_f32_e32 v252, v222, v172
	v_pk_mul_f32 v[172:173], v[250:251], v[168:169]
	v_pk_mul_f32 v[232:233], v[228:229], v[166:167]
	v_pk_mul_f32 v[166:167], v[230:231], v[166:167]
	v_mov_b32_e32 v235, v172
	v_mov_b32_e32 v237, v173
	v_mov_b32_e32 v172, v251
	v_mov_b32_e32 v173, v250
	v_pk_mul_f32 v[168:169], v[172:173], v[168:169]
	v_pk_fma_f32 v[230:231], v[230:231], v[170:171], v[232:233] neg_lo:[0,0,1] neg_hi:[0,0,1]
	v_pk_fma_f32 v[166:167], v[228:229], v[170:171], v[166:167]
	v_floor_f32_e32 v170, v249
	v_mov_b32_e32 v253, v168
	v_mov_b32_e32 v225, v169
	v_fma_f32 v171, v220, v208, -v170
	v_pk_add_f32 v[168:169], v[252:253], v[224:225]
	v_sin_f32_e32 v170, v171
	v_cos_f32_e32 v224, v171
	v_floor_f32_e32 v171, v248
	v_fma_f32 v203, v219, v208, -v171
	v_sin_f32_e32 v171, v203
	v_cos_f32_e32 v225, v203
	v_floor_f32_e32 v203, v244
	v_fma_f32 v203, v218, v208, -v203
	v_floor_f32_e32 v233, v209
	v_cos_f32_e32 v222, v203
	v_sin_f32_e32 v203, v203
	v_fma_f32 v233, v197, v208, -v233
	v_pk_add_f32 v[172:173], v[234:235], v[236:237] neg_lo:[0,1] neg_hi:[0,1]
	v_sin_f32_e32 v237, v233
	v_cos_f32_e32 v236, v233
	v_mul_f32_e32 v234, v203, v176
	v_mul_f32_e32 v252, v222, v176
	v_mov_b32_e32 v176, v165
	v_mul_f32_e32 v232, v222, v164
	v_mul_f32_e32 v250, v203, v164
	v_pk_mul_f32 v[164:165], v[236:237], v[176:177]
	v_pk_mul_f32 v[228:229], v[170:171], v[174:175]
	v_mov_b32_e32 v233, v164
	v_mov_b32_e32 v235, v165
	v_mov_b32_e32 v164, v237
	v_mov_b32_e32 v165, v236
	v_pk_mul_f32 v[164:165], v[164:165], v[176:177]
	v_pk_mul_f32 v[174:175], v[224:225], v[174:175]
	v_mov_b32_e32 v251, v164
	v_mov_b32_e32 v253, v165
	v_pk_fma_f32 v[224:225], v[224:225], v[162:163], v[228:229] neg_lo:[0,0,1] neg_hi:[0,0,1]
	v_pk_add_f32 v[164:165], v[232:233], v[234:235] neg_lo:[0,1] neg_hi:[0,1]
	v_pk_fma_f32 v[174:175], v[170:171], v[162:163], v[174:175]
	v_pk_add_f32 v[176:177], v[250:251], v[252:253]
	v_mov_b32_e32 v170, v230
	v_mov_b32_e32 v171, v231
	v_mov_b32_e32 v162, v224
	v_mov_b32_e32 v163, v225

.LBB0_642:
	v_cvt_pk_bf16_f32 v228, v170, v171
	v_cvt_pk_bf16_f32 v229, v172, v173
	v_add_co_u32_e32 v172, vcc, 0x3000, v204
	s_nop 1
	v_addc_co_u32_e32 v173, vcc, 0, v205, vcc
	v_mbcnt_lo_u32_b32 v0, -1, 0
	v_mbcnt_hi_u32_b32 v0, -1, v0
	v_bfe_u32 v0, v0, 4, 1
	v_mul_u32_u24_e32 v0, 24, v0
	v_lshl_add_u64 v[236:237], v[172:173], 0, v[0:1]
	v_cvt_pk_bf16_f32 v230, v166, v167
	v_cvt_pk_bf16_f32 v231, v168, v169
	s_nop 1
	v_permlane16_swap_b32_e32 v228, v230
	v_permlane16_swap_b32_e32 v229, v231
	global_store_dwordx4 v[236:237], v[228:231], off
	v_cvt_pk_bf16_f32 v232, v162, v163
	v_cvt_pk_bf16_f32 v233, v164, v165
	v_cvt_pk_bf16_f32 v234, v174, v175
	v_cvt_pk_bf16_f32 v235, v176, v177
	s_nop 1
	v_permlane16_swap_b32_e32 v232, v234
	v_permlane16_swap_b32_e32 v233, v235
	global_store_dwordx4 v[236:237], v[232:235], off offset:64
	v_pk_fma_f32 v[162:163], v[64:65], v[202:203], v[160:161] op_sel_hi:[1,0,1]
	v_pk_fma_f32 v[164:165], v[62:63], v[202:203], v[158:159] op_sel_hi:[1,0,1]
	v_mul_f32_e32 v171, v163, v163
	v_mul_f32_e32 v170, v165, v165
	v_pk_fma_f32 v[166:167], v[60:61], v[202:203], v[156:157] op_sel_hi:[1,0,1]
	v_pk_fma_f32 v[168:169], v[58:59], v[202:203], v[154:155] op_sel_hi:[1,0,1]
	v_fmac_f32_e32 v170, v164, v164
	v_fmac_f32_e32 v171, v162, v162
	v_add_f32_e32 v170, v170, v171
	v_mul_f32_e32 v171, v169, v169
	v_mul_f32_e32 v172, v167, v167
	v_fmac_f32_e32 v171, v168, v168
	v_fmac_f32_e32 v172, v166, v166
	v_pk_fma_f32 v[174:175], v[56:57], v[202:203], v[152:153] op_sel_hi:[1,0,1]
	v_pk_fma_f32 v[176:177], v[54:55], v[202:203], v[150:151] op_sel_hi:[1,0,1]
	v_add_f32_e32 v171, v171, v172
	v_add_f32_e32 v170, v170, v171
	v_mul_f32_e32 v171, v177, v177
	v_mul_f32_e32 v172, v175, v175
	v_fmac_f32_e32 v171, v176, v176
	v_fmac_f32_e32 v172, v174, v174
	v_pk_fma_f32 v[206:207], v[52:53], v[202:203], v[148:149] op_sel_hi:[1,0,1]
	v_pk_fma_f32 v[224:225], v[50:51], v[202:203], v[146:147] op_sel_hi:[1,0,1]
	v_add_f32_e32 v171, v171, v172
	v_add_f32_e32 v170, v171, v170
	v_mul_f32_e32 v171, v225, v225
	v_mul_f32_e32 v172, v207, v207
	v_fmac_f32_e32 v171, v224, v224
	v_fmac_f32_e32 v172, v206, v206
	v_add_f32_e32 v171, v171, v172
	v_add_f32_e32 v170, v171, v170
	v_mov_b32_e32 v171, v170
	s_nop 1
	v_permlane16_swap_b32_e32 v170, v171
	v_add_f32_e32 v170, v170, v171
	v_mov_b32_e32 v171, v170
	s_nop 1
	v_permlane32_swap_b32_e32 v170, v171
	v_add_f32_e32 v170, v170, v171
	v_fmamk_f32 v170, v170, 0x3c800000, v223
	v_rsq_f32_e32 v222, v170
	v_mov_b64_e32 v[202:203], v[192:193]
	v_mov_b64_e32 v[204:205], v[194:195]
	s_and_b64 vcc, exec, s[44:45]
	v_pk_mul_f32 v[164:165], v[164:165], v[222:223] op_sel_hi:[1,0]
	v_pk_mul_f32 v[162:163], v[162:163], v[222:223] op_sel_hi:[1,0]
	v_pk_mul_f32 v[170:171], v[130:131], v[164:165]
	v_pk_mul_f32 v[172:173], v[132:133], v[162:163]
	v_pk_mul_f32 v[162:163], v[168:169], v[222:223] op_sel_hi:[1,0]
	v_pk_mul_f32 v[164:165], v[166:167], v[222:223] op_sel_hi:[1,0]
	v_pk_mul_f32 v[166:167], v[134:135], v[162:163]
	v_pk_mul_f32 v[168:169], v[136:137], v[164:165]
	v_pk_mul_f32 v[162:163], v[176:177], v[222:223] op_sel_hi:[1,0]
	v_pk_mul_f32 v[164:165], v[174:175], v[222:223] op_sel_hi:[1,0]
	v_pk_mul_f32 v[174:175], v[224:225], v[222:223] op_sel_hi:[1,0]
	v_pk_mul_f32 v[176:177], v[206:207], v[222:223] op_sel_hi:[1,0]
	v_pk_mul_f32 v[164:165], v[140:141], v[164:165]
	v_pk_mul_f32 v[162:163], v[138:139], v[162:163]
	v_pk_mul_f32 v[176:177], v[144:145], v[176:177]
	v_pk_mul_f32 v[174:175], v[142:143], v[174:175]
	s_cbranch_vccnz .LBB0_644
	v_add_u32_e32 v206, 0x80, v216
	v_ashrrev_i32_e32 v206, 6, v206
	v_cvt_f32_i32_e32 v222, v206
	v_mul_f32_e32 v206, v220, v222
	v_mul_f32_e32 v207, v219, v222
	v_floor_f32_e32 v206, v206
	v_floor_f32_e32 v207, v207
	v_fma_f32 v224, v220, v222, -v206
	v_fma_f32 v225, v219, v222, -v207
	v_sin_f32_e32 v206, v224
	v_cos_f32_e32 v224, v224
	v_sin_f32_e32 v207, v225
	v_cos_f32_e32 v225, v225
	v_mul_f32_e32 v228, v218, v222
	v_floor_f32_e32 v228, v228
	v_fma_f32 v228, v218, v222, -v228
	v_cos_f32_e32 v231, v228
	v_sin_f32_e32 v233, v228
	v_pk_mul_f32 v[228:229], v[206:207], v[166:167]
	v_pk_mul_f32 v[166:167], v[224:225], v[166:167]
	v_mul_f32_e32 v234, v197, v222
	v_floor_f32_e32 v234, v234
	v_pk_fma_f32 v[224:225], v[224:225], v[170:171], v[228:229] neg_lo:[0,0,1] neg_hi:[0,0,1]
	v_pk_fma_f32 v[166:167], v[206:207], v[170:171], v[166:167]
	v_floor_f32_e32 v170, v201
	v_fma_f32 v222, v197, v222, -v234
	v_fma_f32 v171, v220, v199, -v170
	v_sin_f32_e32 v235, v222
	v_cos_f32_e32 v234, v222
	v_sin_f32_e32 v170, v171
	v_cos_f32_e32 v206, v171
	v_floor_f32_e32 v171, v239
	v_fma_f32 v201, v219, v199, -v171
	v_sin_f32_e32 v171, v201
	v_cos_f32_e32 v207, v201
	v_floor_f32_e32 v201, v221
	v_mul_f32_e32 v232, v233, v168
	v_mul_f32_e32 v250, v231, v168
	v_mov_b32_e32 v168, v173
	v_fma_f32 v201, v218, v199, -v201
	v_floor_f32_e32 v222, v240
	v_mul_f32_e32 v230, v231, v172
	v_mul_f32_e32 v236, v233, v172
	v_pk_mul_f32 v[172:173], v[234:235], v[168:169]
	v_cos_f32_e32 v221, v201
	v_sin_f32_e32 v201, v201
	v_fma_f32 v199, v197, v199, -v222
	v_mov_b32_e32 v231, v172
	v_mov_b32_e32 v233, v173
	v_mov_b32_e32 v172, v235
	v_mov_b32_e32 v173, v234
	v_sin_f32_e32 v235, v199
	v_cos_f32_e32 v234, v199
	v_pk_mul_f32 v[168:169], v[172:173], v[168:169]
	v_pk_add_f32 v[172:173], v[230:231], v[232:233] neg_lo:[0,1] neg_hi:[0,1]
	v_mov_b32_e32 v237, v168
	v_mov_b32_e32 v251, v169
	v_mul_f32_e32 v232, v201, v176
	v_mul_f32_e32 v238, v221, v176
	v_mov_b32_e32 v176, v165
	v_pk_add_f32 v[168:169], v[236:237], v[250:251]
	v_mul_f32_e32 v230, v221, v164
	v_mul_f32_e32 v236, v201, v164
	v_pk_mul_f32 v[164:165], v[234:235], v[176:177]
	v_pk_mul_f32 v[228:229], v[170:171], v[174:175]
	v_mov_b32_e32 v231, v164
	v_mov_b32_e32 v233, v165
	v_mov_b32_e32 v164, v235
	v_mov_b32_e32 v165, v234
	v_pk_mul_f32 v[164:165], v[164:165], v[176:177]
	v_pk_mul_f32 v[174:175], v[206:207], v[174:175]
	v_mov_b32_e32 v237, v164
	v_mov_b32_e32 v239, v165
	v_pk_fma_f32 v[206:207], v[206:207], v[162:163], v[228:229] neg_lo:[0,0,1] neg_hi:[0,0,1]
	v_pk_add_f32 v[164:165], v[230:231], v[232:233] neg_lo:[0,1] neg_hi:[0,1]
	v_pk_fma_f32 v[174:175], v[170:171], v[162:163], v[174:175]
	v_pk_add_f32 v[176:177], v[236:237], v[238:239]
	v_mov_b32_e32 v170, v224
	v_mov_b32_e32 v171, v225
	v_mov_b32_e32 v162, v206
	v_mov_b32_e32 v163, v207

.LBB0_646:
	v_cvt_pk_bf16_f32 v228, v170, v171
	v_cvt_pk_bf16_f32 v229, v172, v173
	v_add_co_u32_e32 v172, vcc, 0x8000, v202
	v_pk_fma_f32 v[204:205], v[36:37], v[200:201], v[148:149] op_sel_hi:[1,0,1]
	s_nop 0
	v_addc_co_u32_e32 v173, vcc, 0, v203, vcc
	v_mbcnt_lo_u32_b32 v0, -1, 0
	v_mbcnt_hi_u32_b32 v0, -1, v0
	v_bfe_u32 v0, v0, 4, 1
	v_mul_u32_u24_e32 v0, 24, v0
	v_lshl_add_u64 v[236:237], v[172:173], 0, v[0:1]
	v_cvt_pk_bf16_f32 v230, v166, v167
	v_cvt_pk_bf16_f32 v231, v168, v169
	s_nop 1
	v_permlane16_swap_b32_e32 v228, v230
	v_permlane16_swap_b32_e32 v229, v231
	global_store_dwordx4 v[236:237], v[228:231], off
	v_cvt_pk_bf16_f32 v232, v162, v163
	v_cvt_pk_bf16_f32 v233, v164, v165
	v_cvt_pk_bf16_f32 v234, v174, v175
	v_cvt_pk_bf16_f32 v235, v176, v177
	s_nop 1
	v_permlane16_swap_b32_e32 v232, v234
	v_permlane16_swap_b32_e32 v233, v235
	global_store_dwordx4 v[236:237], v[232:235], off offset:64
	v_pk_fma_f32 v[162:163], v[48:49], v[200:201], v[160:161] op_sel_hi:[1,0,1]
	v_pk_fma_f32 v[164:165], v[46:47], v[200:201], v[158:159] op_sel_hi:[1,0,1]
	v_mul_f32_e32 v171, v163, v163
	v_mul_f32_e32 v170, v165, v165
	v_pk_fma_f32 v[166:167], v[44:45], v[200:201], v[156:157] op_sel_hi:[1,0,1]
	v_pk_fma_f32 v[168:169], v[42:43], v[200:201], v[154:155] op_sel_hi:[1,0,1]
	v_fmac_f32_e32 v170, v164, v164
	v_fmac_f32_e32 v171, v162, v162
	v_add_f32_e32 v170, v170, v171
	v_mul_f32_e32 v171, v169, v169
	v_mul_f32_e32 v172, v167, v167
	v_fmac_f32_e32 v171, v168, v168
	v_fmac_f32_e32 v172, v166, v166
	v_pk_fma_f32 v[174:175], v[40:41], v[200:201], v[152:153] op_sel_hi:[1,0,1]
	v_pk_fma_f32 v[176:177], v[38:39], v[200:201], v[150:151] op_sel_hi:[1,0,1]
	v_add_f32_e32 v171, v171, v172
	v_add_f32_e32 v170, v170, v171
	v_mul_f32_e32 v171, v177, v177
	v_mul_f32_e32 v172, v175, v175
	v_fmac_f32_e32 v171, v176, v176
	v_fmac_f32_e32 v172, v174, v174
	v_pk_fma_f32 v[206:207], v[34:35], v[200:201], v[146:147] op_sel_hi:[1,0,1]
	v_add_f32_e32 v171, v171, v172
	v_add_f32_e32 v170, v171, v170
	v_mul_f32_e32 v171, v207, v207
	v_mul_f32_e32 v172, v205, v205
	v_fmac_f32_e32 v171, v206, v206
	v_fmac_f32_e32 v172, v204, v204
	v_add_f32_e32 v171, v171, v172
	v_add_f32_e32 v170, v171, v170
	v_mov_b32_e32 v171, v170
	s_nop 1
	v_permlane16_swap_b32_e32 v170, v171
	v_add_f32_e32 v170, v170, v171
	v_mov_b32_e32 v171, v170
	s_nop 1
	v_permlane32_swap_b32_e32 v170, v171
	v_add_f32_e32 v170, v170, v171
	v_fmamk_f32 v170, v170, 0x3c800000, v223
	v_rsq_f32_e32 v222, v170
	v_mov_b64_e32 v[202:203], v[194:195]
	v_mov_b64_e32 v[200:201], v[192:193]
	s_and_b64 vcc, exec, s[44:45]
	v_pk_mul_f32 v[164:165], v[164:165], v[222:223] op_sel_hi:[1,0]
	v_pk_mul_f32 v[162:163], v[162:163], v[222:223] op_sel_hi:[1,0]
	v_pk_mul_f32 v[170:171], v[130:131], v[164:165]
	v_pk_mul_f32 v[172:173], v[132:133], v[162:163]
	v_pk_mul_f32 v[162:163], v[168:169], v[222:223] op_sel_hi:[1,0]
	v_pk_mul_f32 v[164:165], v[166:167], v[222:223] op_sel_hi:[1,0]
	v_pk_mul_f32 v[166:167], v[134:135], v[162:163]
	v_pk_mul_f32 v[168:169], v[136:137], v[164:165]
	v_pk_mul_f32 v[162:163], v[176:177], v[222:223] op_sel_hi:[1,0]
	v_pk_mul_f32 v[164:165], v[174:175], v[222:223] op_sel_hi:[1,0]
	v_pk_mul_f32 v[174:175], v[206:207], v[222:223] op_sel_hi:[1,0]
	v_pk_mul_f32 v[176:177], v[204:205], v[222:223] op_sel_hi:[1,0]
	v_pk_mul_f32 v[164:165], v[140:141], v[164:165]
	v_pk_mul_f32 v[162:163], v[138:139], v[162:163]
	v_pk_mul_f32 v[176:177], v[144:145], v[176:177]
	v_pk_mul_f32 v[174:175], v[142:143], v[174:175]
	v_mov_b32_e32 v238, 0xd00000
	v_mov_b32_e32 v239, 0xd05000
	s_cbranch_vccnz .LBB0_648
	v_add_u32_e32 v199, 0x90, v216
	v_ashrrev_i32_e32 v199, 6, v199
	v_cvt_f32_i32_e32 v199, v199
	v_floor_f32_e32 v213, v213
	v_mul_f32_e32 v204, v220, v199
	v_mul_f32_e32 v205, v219, v199
	v_floor_f32_e32 v204, v204
	v_floor_f32_e32 v205, v205
	v_fma_f32 v206, v220, v199, -v204
	v_fma_f32 v207, v219, v199, -v205
	v_sin_f32_e32 v204, v206
	v_cos_f32_e32 v206, v206
	v_sin_f32_e32 v205, v207
	v_cos_f32_e32 v207, v207
	v_mul_f32_e32 v221, v218, v199
	v_floor_f32_e32 v221, v221
	v_pk_mul_f32 v[224:225], v[204:205], v[166:167]
	v_pk_mul_f32 v[166:167], v[206:207], v[166:167]
	v_mul_f32_e32 v229, v197, v199
	v_fma_f32 v221, v218, v199, -v221
	v_floor_f32_e32 v229, v229
	v_pk_fma_f32 v[206:207], v[206:207], v[170:171], v[224:225] neg_lo:[0,0,1] neg_hi:[0,0,1]
	v_pk_fma_f32 v[166:167], v[204:205], v[170:171], v[166:167]
	v_floor_f32_e32 v170, v245
	v_cos_f32_e32 v222, v221
	v_sin_f32_e32 v221, v221
	v_fma_f32 v199, v197, v199, -v229
	v_fma_f32 v171, v220, v212, -v170
	v_sin_f32_e32 v233, v199
	v_cos_f32_e32 v232, v199
	v_sin_f32_e32 v170, v171
	v_cos_f32_e32 v204, v171
	v_floor_f32_e32 v171, v243
	v_fma_f32 v199, v219, v212, -v171
	v_sin_f32_e32 v171, v199
	v_cos_f32_e32 v205, v199
	v_floor_f32_e32 v199, v241
	v_mul_f32_e32 v230, v221, v168
	v_mul_f32_e32 v236, v222, v168
	v_mov_b32_e32 v168, v173
	v_fma_f32 v199, v218, v212, -v199
	v_mul_f32_e32 v228, v222, v172
	v_mul_f32_e32 v234, v221, v172
	v_pk_mul_f32 v[172:173], v[232:233], v[168:169]
	v_cos_f32_e32 v221, v199
	v_sin_f32_e32 v199, v199
	v_fma_f32 v212, v197, v212, -v213
	v_mov_b32_e32 v229, v172
	v_mov_b32_e32 v231, v173
	v_mov_b32_e32 v172, v233
	v_mov_b32_e32 v173, v232
	v_sin_f32_e32 v213, v212
	v_cos_f32_e32 v212, v212
	v_pk_mul_f32 v[168:169], v[172:173], v[168:169]
	v_pk_add_f32 v[172:173], v[228:229], v[230:231] neg_lo:[0,1] neg_hi:[0,1]
	v_mov_b32_e32 v235, v168
	v_mov_b32_e32 v237, v169
	v_pk_add_f32 v[168:169], v[234:235], v[236:237]
	v_mul_f32_e32 v230, v199, v176
	v_mul_f32_e32 v234, v221, v176
	v_mov_b32_e32 v176, v165
	v_mul_f32_e32 v228, v221, v164
	v_mul_f32_e32 v232, v199, v164
	v_pk_mul_f32 v[164:165], v[212:213], v[176:177]
	v_pk_mul_f32 v[224:225], v[170:171], v[174:175]
	v_mov_b32_e32 v229, v164
	v_mov_b32_e32 v231, v165
	v_mov_b32_e32 v164, v213
	v_mov_b32_e32 v165, v212
	v_pk_mul_f32 v[164:165], v[164:165], v[176:177]
	v_pk_mul_f32 v[174:175], v[204:205], v[174:175]
	v_mov_b32_e32 v233, v164
	v_mov_b32_e32 v235, v165
	v_pk_fma_f32 v[204:205], v[204:205], v[162:163], v[224:225] neg_lo:[0,0,1] neg_hi:[0,0,1]
	v_pk_add_f32 v[164:165], v[228:229], v[230:231] neg_lo:[0,1] neg_hi:[0,1]
	v_pk_fma_f32 v[174:175], v[170:171], v[162:163], v[174:175]
	v_pk_add_f32 v[176:177], v[232:233], v[234:235]
	v_mov_b32_e32 v170, v206
	v_mov_b32_e32 v171, v207
	v_mov_b32_e32 v162, v204
	v_mov_b32_e32 v163, v205

.LBB0_650:
	v_cvt_pk_bf16_f32 v228, v170, v171
	v_cvt_pk_bf16_f32 v229, v172, v173
	v_add_co_u32_e32 v172, vcc, 0x9000, v200
	s_nop 1
	v_addc_co_u32_e32 v173, vcc, 0, v201, vcc
	v_mbcnt_lo_u32_b32 v0, -1, 0
	v_mbcnt_hi_u32_b32 v0, -1, v0
	v_bfe_u32 v0, v0, 4, 1
	v_mul_u32_u24_e32 v0, 24, v0
	v_lshl_add_u64 v[236:237], v[172:173], 0, v[0:1]
	v_cvt_pk_bf16_f32 v230, v166, v167
	v_cvt_pk_bf16_f32 v231, v168, v169
	s_nop 1
	v_permlane16_swap_b32_e32 v228, v230
	v_permlane16_swap_b32_e32 v229, v231
	global_store_dwordx4 v[236:237], v[228:231], off
	v_cvt_pk_bf16_f32 v232, v162, v163
	v_cvt_pk_bf16_f32 v233, v164, v165
	v_cvt_pk_bf16_f32 v234, v174, v175
	v_cvt_pk_bf16_f32 v235, v176, v177
	s_nop 1
	v_permlane16_swap_b32_e32 v232, v234
	v_permlane16_swap_b32_e32 v233, v235
	global_store_dwordx4 v[236:237], v[232:235], off offset:64
	v_pk_fma_f32 v[162:163], v[32:33], v[198:199], v[160:161] op_sel_hi:[1,0,1]
	v_pk_fma_f32 v[164:165], v[30:31], v[198:199], v[158:159] op_sel_hi:[1,0,1]
	v_mul_f32_e32 v171, v163, v163
	v_mul_f32_e32 v170, v165, v165
	v_pk_fma_f32 v[166:167], v[28:29], v[198:199], v[156:157] op_sel_hi:[1,0,1]
	v_pk_fma_f32 v[168:169], v[26:27], v[198:199], v[154:155] op_sel_hi:[1,0,1]
	v_fmac_f32_e32 v170, v164, v164
	v_fmac_f32_e32 v171, v162, v162
	v_add_f32_e32 v170, v170, v171
	v_mul_f32_e32 v171, v169, v169
	v_mul_f32_e32 v172, v167, v167
	v_fmac_f32_e32 v171, v168, v168
	v_fmac_f32_e32 v172, v166, v166
	v_pk_fma_f32 v[202:203], v[24:25], v[198:199], v[152:153] op_sel_hi:[1,0,1]
	v_pk_fma_f32 v[204:205], v[22:23], v[198:199], v[150:151] op_sel_hi:[1,0,1]
	v_add_f32_e32 v171, v171, v172
	v_add_f32_e32 v170, v170, v171
	v_mul_f32_e32 v171, v205, v205
	v_mul_f32_e32 v172, v203, v203
	v_fmac_f32_e32 v171, v204, v204
	v_fmac_f32_e32 v172, v202, v202
	v_pk_fma_f32 v[206:207], v[20:21], v[198:199], v[148:149] op_sel_hi:[1,0,1]
	v_pk_fma_f32 v[212:213], v[18:19], v[198:199], v[146:147] op_sel_hi:[1,0,1]
	v_add_f32_e32 v171, v171, v172
	v_add_f32_e32 v170, v171, v170
	v_mul_f32_e32 v171, v213, v213
	v_mul_f32_e32 v172, v207, v207
	v_fmac_f32_e32 v171, v212, v212
	v_fmac_f32_e32 v172, v206, v206
	v_add_f32_e32 v171, v171, v172
	v_add_f32_e32 v170, v171, v170
	v_mov_b32_e32 v171, v170
	s_nop 1
	v_permlane16_swap_b32_e32 v170, v171
	v_add_f32_e32 v170, v170, v171
	v_mov_b32_e32 v171, v170
	s_nop 1
	v_permlane32_swap_b32_e32 v170, v171
	v_add_f32_e32 v170, v170, v171
	v_fmamk_f32 v170, v170, 0x3c800000, v223
	v_rsq_f32_e32 v222, v170
	v_mov_b64_e32 v[200:201], v[194:195]
	v_mov_b64_e32 v[198:199], v[192:193]
	s_and_b64 vcc, exec, s[44:45]
	v_pk_mul_f32 v[164:165], v[164:165], v[222:223] op_sel_hi:[1,0]
	v_pk_mul_f32 v[162:163], v[162:163], v[222:223] op_sel_hi:[1,0]
	v_pk_mul_f32 v[174:175], v[130:131], v[164:165]
	v_pk_mul_f32 v[176:177], v[132:133], v[162:163]
	v_pk_mul_f32 v[162:163], v[168:169], v[222:223] op_sel_hi:[1,0]
	v_pk_mul_f32 v[164:165], v[166:167], v[222:223] op_sel_hi:[1,0]
	v_pk_mul_f32 v[170:171], v[134:135], v[162:163]
	v_pk_mul_f32 v[172:173], v[136:137], v[164:165]
	v_pk_mul_f32 v[162:163], v[204:205], v[222:223] op_sel_hi:[1,0]
	v_pk_mul_f32 v[164:165], v[202:203], v[222:223] op_sel_hi:[1,0]
	v_pk_mul_f32 v[166:167], v[138:139], v[162:163]
	v_pk_mul_f32 v[168:169], v[140:141], v[164:165]
	v_pk_mul_f32 v[162:163], v[212:213], v[222:223] op_sel_hi:[1,0]
	v_pk_mul_f32 v[164:165], v[206:207], v[222:223] op_sel_hi:[1,0]
	v_pk_mul_f32 v[162:163], v[142:143], v[162:163]
	v_pk_mul_f32 v[164:165], v[144:145], v[164:165]
	s_cbranch_vccnz .LBB0_652
	v_add_u32_e32 v202, 0xa0, v216
	v_ashrrev_i32_e32 v202, 6, v202
	v_cvt_f32_i32_e32 v213, v202
	v_floor_f32_e32 v211, v211
	v_mul_f32_e32 v202, v220, v213
	v_mul_f32_e32 v203, v219, v213
	v_floor_f32_e32 v202, v202
	v_floor_f32_e32 v203, v203
	v_mul_f32_e32 v206, v218, v213
	v_fma_f32 v204, v220, v213, -v202
	v_fma_f32 v205, v219, v213, -v203
	v_floor_f32_e32 v206, v206
	v_mul_f32_e32 v225, v197, v213
	v_sin_f32_e32 v202, v204
	v_cos_f32_e32 v204, v204
	v_sin_f32_e32 v203, v205
	v_cos_f32_e32 v205, v205
	v_fma_f32 v206, v218, v213, -v206
	v_floor_f32_e32 v225, v225
	v_cos_f32_e32 v221, v206
	v_sin_f32_e32 v222, v206
	v_fma_f32 v213, v197, v213, -v225
	v_sin_f32_e32 v229, v213
	v_cos_f32_e32 v228, v213
	v_pk_mul_f32 v[206:207], v[202:203], v[170:171]
	v_pk_mul_f32 v[170:171], v[204:205], v[170:171]
	v_mul_f32_e32 v224, v222, v172
	v_mul_f32_e32 v232, v221, v172
	v_mov_b32_e32 v172, v177
	v_pk_fma_f32 v[204:205], v[204:205], v[174:175], v[206:207] neg_lo:[0,0,1] neg_hi:[0,0,1]
	v_pk_fma_f32 v[170:171], v[202:203], v[174:175], v[170:171]
	v_floor_f32_e32 v174, v247
	v_mul_f32_e32 v212, v221, v176
	v_mul_f32_e32 v230, v222, v176
	v_pk_mul_f32 v[176:177], v[228:229], v[172:173]
	v_fma_f32 v175, v220, v210, -v174
	v_floor_f32_e32 v206, v242
	v_mov_b32_e32 v213, v176
	v_mov_b32_e32 v225, v177
	v_mov_b32_e32 v176, v229
	v_mov_b32_e32 v177, v228
	v_sin_f32_e32 v174, v175
	v_cos_f32_e32 v202, v175
	v_floor_f32_e32 v175, v246
	v_fma_f32 v206, v218, v210, -v206
	v_pk_mul_f32 v[172:173], v[176:177], v[172:173]
	v_pk_add_f32 v[176:177], v[212:213], v[224:225] neg_lo:[0,1] neg_hi:[0,1]
	v_fma_f32 v203, v219, v210, -v175
	v_cos_f32_e32 v213, v206
	v_sin_f32_e32 v221, v206
	v_fma_f32 v210, v197, v210, -v211
	v_sin_f32_e32 v211, v210
	v_cos_f32_e32 v210, v210
	v_mov_b32_e32 v231, v172
	v_mov_b32_e32 v233, v173
	v_sin_f32_e32 v175, v203
	v_pk_add_f32 v[172:173], v[230:231], v[232:233]
	v_cos_f32_e32 v203, v203
	v_mul_f32_e32 v224, v221, v164
	v_mul_f32_e32 v230, v213, v164
	v_mov_b32_e32 v164, v169
	v_mul_f32_e32 v212, v213, v168
	v_mul_f32_e32 v228, v221, v168
	v_pk_mul_f32 v[168:169], v[210:211], v[164:165]
	v_pk_mul_f32 v[206:207], v[174:175], v[162:163]
	v_mov_b32_e32 v213, v168
	v_mov_b32_e32 v225, v169
	v_mov_b32_e32 v168, v211
	v_mov_b32_e32 v169, v210
	v_pk_mul_f32 v[164:165], v[168:169], v[164:165]
	v_pk_mul_f32 v[162:163], v[202:203], v[162:163]
	v_mov_b32_e32 v229, v164
	v_mov_b32_e32 v231, v165
	v_pk_fma_f32 v[202:203], v[202:203], v[166:167], v[206:207] neg_lo:[0,0,1] neg_hi:[0,0,1]
	v_pk_add_f32 v[168:169], v[212:213], v[224:225] neg_lo:[0,1] neg_hi:[0,1]
	v_pk_fma_f32 v[162:163], v[174:175], v[166:167], v[162:163]
	v_pk_add_f32 v[164:165], v[228:229], v[230:231]
	v_mov_b32_e32 v174, v204
	v_mov_b32_e32 v175, v205
	v_mov_b32_e32 v166, v202
	v_mov_b32_e32 v167, v203

.LBB0_654:
	v_cvt_pk_bf16_f32 v228, v174, v175
	v_cvt_pk_bf16_f32 v229, v176, v177
	v_add_co_u32_e32 v176, vcc, 0xa000, v198
	v_pk_fma_f32 v[160:161], v[16:17], v[196:197], v[160:161] op_sel_hi:[1,0,1]
	s_nop 0
	v_addc_co_u32_e32 v177, vcc, 0, v199, vcc
	v_pk_fma_f32 v[158:159], v[14:15], v[196:197], v[158:159] op_sel_hi:[1,0,1]
	v_mbcnt_lo_u32_b32 v0, -1, 0
	v_mbcnt_hi_u32_b32 v0, -1, v0
	v_bfe_u32 v0, v0, 4, 1
	v_mul_u32_u24_e32 v0, 24, v0
	v_lshl_add_u64 v[236:237], v[176:177], 0, v[0:1]
	v_cvt_pk_bf16_f32 v230, v170, v171
	v_cvt_pk_bf16_f32 v231, v172, v173
	s_nop 1
	v_permlane16_swap_b32_e32 v228, v230
	v_permlane16_swap_b32_e32 v229, v231
	global_store_dwordx4 v[236:237], v[228:231], off
	v_cvt_pk_bf16_f32 v232, v166, v167
	v_cvt_pk_bf16_f32 v233, v168, v169
	v_pk_fma_f32 v[168:169], v[2:3], v[196:197], v[146:147] op_sel_hi:[1,0,1]
	v_mul_f32_e32 v146, v159, v159
	v_mul_f32_e32 v147, v161, v161
	v_pk_fma_f32 v[156:157], v[12:13], v[196:197], v[156:157] op_sel_hi:[1,0,1]
	v_pk_fma_f32 v[154:155], v[10:11], v[196:197], v[154:155] op_sel_hi:[1,0,1]
	v_fmac_f32_e32 v146, v158, v158
	v_fmac_f32_e32 v147, v160, v160
	v_pk_fma_f32 v[166:167], v[4:5], v[196:197], v[148:149] op_sel_hi:[1,0,1]
	v_add_f32_e32 v146, v146, v147
	v_mul_f32_e32 v147, v155, v155
	v_mul_f32_e32 v148, v157, v157
	v_fmac_f32_e32 v147, v154, v154
	v_fmac_f32_e32 v148, v156, v156
	v_pk_fma_f32 v[152:153], v[8:9], v[196:197], v[152:153] op_sel_hi:[1,0,1]
	v_pk_fma_f32 v[150:151], v[6:7], v[196:197], v[150:151] op_sel_hi:[1,0,1]
	v_add_f32_e32 v147, v147, v148
	v_add_f32_e32 v146, v146, v147
	v_mul_f32_e32 v147, v151, v151
	v_mul_f32_e32 v148, v153, v153
	v_fmac_f32_e32 v147, v150, v150
	v_fmac_f32_e32 v148, v152, v152
	v_add_f32_e32 v147, v147, v148
	v_add_f32_e32 v146, v147, v146
	v_mul_f32_e32 v147, v169, v169
	v_mul_f32_e32 v148, v167, v167
	v_fmac_f32_e32 v147, v168, v168
	v_fmac_f32_e32 v148, v166, v166
	v_add_f32_e32 v147, v147, v148
	v_add_f32_e32 v146, v147, v146
	v_mov_b32_e32 v147, v146
	s_nop 1
	v_permlane16_swap_b32_e32 v146, v147
	v_add_f32_e32 v146, v146, v147
	v_mov_b32_e32 v147, v146
	s_nop 1
	v_permlane32_swap_b32_e32 v146, v147
	v_add_f32_e32 v146, v146, v147
	v_fmamk_f32 v146, v146, 0x3c800000, v223
	v_rsq_f32_e32 v170, v146
	s_and_b64 vcc, exec, s[44:45]
	v_mov_b32_e32 v226, 0x260
	v_cvt_pk_bf16_f32 v234, v162, v163
	v_pk_mul_f32 v[146:147], v[158:159], v[170:171] op_sel_hi:[1,0]
	v_pk_mul_f32 v[148:149], v[160:161], v[170:171] op_sel_hi:[1,0]
	v_pk_mul_f32 v[146:147], v[130:131], v[146:147]
	v_pk_mul_f32 v[148:149], v[132:133], v[148:149]
	v_pk_mul_f32 v[130:131], v[154:155], v[170:171] op_sel_hi:[1,0]
	v_pk_mul_f32 v[132:133], v[156:157], v[170:171] op_sel_hi:[1,0]
	v_pk_mul_f32 v[134:135], v[134:135], v[130:131]
	v_pk_mul_f32 v[136:137], v[136:137], v[132:133]
	v_pk_mul_f32 v[130:131], v[150:151], v[170:171] op_sel_hi:[1,0]
	v_pk_mul_f32 v[132:133], v[152:153], v[170:171] op_sel_hi:[1,0]
	v_pk_mul_f32 v[130:131], v[138:139], v[130:131]
	v_pk_mul_f32 v[132:133], v[140:141], v[132:133]
	v_pk_mul_f32 v[138:139], v[168:169], v[170:171] op_sel_hi:[1,0]
	v_pk_mul_f32 v[140:141], v[166:167], v[170:171] op_sel_hi:[1,0]
	v_pk_mul_f32 v[138:139], v[142:143], v[138:139]
	v_pk_mul_f32 v[140:141], v[144:145], v[140:141]
	v_cvt_pk_bf16_f32 v235, v164, v165
	s_nop 1
	v_permlane16_swap_b32_e32 v232, v234
	v_permlane16_swap_b32_e32 v233, v235
	global_store_dwordx4 v[236:237], v[232:235], off offset:64
	s_cbranch_vccnz .LBB0_656
	v_add_u32_e32 v142, 0xb0, v216
	v_ashrrev_i32_e32 v142, 6, v142
	v_cvt_f32_i32_e32 v153, v142
	v_mul_f32_e32 v142, v220, v153
	v_mul_f32_e32 v143, v219, v153
	v_mul_f32_e32 v150, v218, v153
	v_floor_f32_e32 v142, v142
	v_floor_f32_e32 v143, v143
	v_floor_f32_e32 v150, v150
	v_mul_f32_e32 v156, v197, v153
	v_fma_f32 v144, v220, v153, -v142
	v_fma_f32 v145, v219, v153, -v143
	v_fma_f32 v150, v218, v153, -v150
	v_floor_f32_e32 v156, v156
	v_sin_f32_e32 v142, v144
	v_sin_f32_e32 v143, v145
	v_cos_f32_e32 v155, v150
	v_sin_f32_e32 v158, v150
	v_fma_f32 v153, v197, v153, -v156
	v_cos_f32_e32 v144, v144
	v_cos_f32_e32 v145, v145
	v_sin_f32_e32 v157, v153
	v_cos_f32_e32 v156, v153
	v_pk_mul_f32 v[150:151], v[142:143], v[134:135]
	v_mul_f32_e32 v154, v158, v136
	v_mul_f32_e32 v160, v155, v136
	v_mov_b32_e32 v136, v149
	v_pk_mul_f32 v[134:135], v[144:145], v[134:135]
	v_mul_f32_e32 v152, v155, v148
	v_mul_f32_e32 v158, v158, v148
	v_pk_mul_f32 v[148:149], v[156:157], v[136:137]
	v_pk_fma_f32 v[144:145], v[144:145], v[146:147], v[150:151] neg_lo:[0,0,1] neg_hi:[0,0,1]
	v_floor_f32_e32 v150, v244
	v_mov_b32_e32 v153, v148
	v_mov_b32_e32 v155, v149
	v_mov_b32_e32 v148, v157
	v_mov_b32_e32 v149, v156
	v_pk_fma_f32 v[134:135], v[142:143], v[146:147], v[134:135]
	v_floor_f32_e32 v142, v249
	v_fma_f32 v150, v218, v208, -v150
	v_floor_f32_e32 v156, v209
	v_pk_mul_f32 v[136:137], v[148:149], v[136:137]
	v_pk_add_f32 v[148:149], v[152:153], v[154:155] neg_lo:[0,1] neg_hi:[0,1]
	v_fma_f32 v143, v220, v208, -v142
	v_cos_f32_e32 v153, v150
	v_sin_f32_e32 v155, v150
	v_fma_f32 v156, v197, v208, -v156
	v_sin_f32_e32 v142, v143
	v_cos_f32_e32 v146, v143
	v_floor_f32_e32 v143, v248
	v_sin_f32_e32 v157, v156
	v_cos_f32_e32 v156, v156
	v_fma_f32 v147, v219, v208, -v143
	v_mov_b32_e32 v159, v136
	v_mov_b32_e32 v161, v137
	v_sin_f32_e32 v143, v147
	v_pk_add_f32 v[136:137], v[158:159], v[160:161]
	v_cos_f32_e32 v147, v147
	v_mul_f32_e32 v154, v155, v140
	v_mul_f32_e32 v160, v153, v140
	v_mov_b32_e32 v140, v133
	v_mul_f32_e32 v152, v153, v132
	v_mul_f32_e32 v158, v155, v132
	v_pk_mul_f32 v[132:133], v[156:157], v[140:141]
	v_pk_mul_f32 v[150:151], v[142:143], v[138:139]
	v_mov_b32_e32 v153, v132
	v_mov_b32_e32 v155, v133
	v_mov_b32_e32 v132, v157
	v_mov_b32_e32 v133, v156
	v_pk_mul_f32 v[132:133], v[132:133], v[140:141]
	v_pk_mul_f32 v[138:139], v[146:147], v[138:139]
	v_mov_b32_e32 v159, v132
	v_mov_b32_e32 v161, v133
	v_pk_fma_f32 v[150:151], v[146:147], v[130:131], v[150:151] neg_lo:[0,0,1] neg_hi:[0,0,1]
	v_pk_add_f32 v[132:133], v[152:153], v[154:155] neg_lo:[0,1] neg_hi:[0,1]
	v_pk_fma_f32 v[138:139], v[142:143], v[130:131], v[138:139]
	v_pk_add_f32 v[140:141], v[158:159], v[160:161]
	v_mov_b32_e32 v146, v144
	v_mov_b32_e32 v147, v145
	v_mov_b32_e32 v130, v150
	v_mov_b32_e32 v131, v151

.LBB0_658:
	v_add_co_u32_e32 v144, vcc, 0xb000, v192
	v_cvt_pk_bf16_f32 v228, v146, v147
	v_cvt_pk_bf16_f32 v229, v148, v149
	s_nop 1
	v_addc_co_u32_e32 v145, vcc, 0, v193, vcc
	v_mbcnt_lo_u32_b32 v0, -1, 0
	v_mbcnt_hi_u32_b32 v0, -1, v0
	v_bfe_u32 v0, v0, 4, 1
	v_mul_u32_u24_e32 v0, 24, v0
	v_lshl_add_u64 v[236:237], v[144:145], 0, v[0:1]
	v_cvt_pk_bf16_f32 v230, v134, v135
	v_cvt_pk_bf16_f32 v231, v136, v137
	s_nop 1
	v_permlane16_swap_b32_e32 v228, v230
	v_permlane16_swap_b32_e32 v229, v231
	global_store_dwordx4 v[236:237], v[228:231], off
	v_cvt_pk_bf16_f32 v232, v130, v131
	v_cvt_pk_bf16_f32 v233, v132, v133
	v_cvt_pk_bf16_f32 v234, v138, v139
	v_cvt_pk_bf16_f32 v235, v140, v141
	s_nop 1
	v_permlane16_swap_b32_e32 v232, v234
	v_permlane16_swap_b32_e32 v233, v235
	global_store_dwordx4 v[236:237], v[232:235], off offset:64
